# v114 + BF16S epilogue head: 16 rstd butterflies via v_permlane16/32_swap instead of ds_bpermute
# baseline (speedup 1.0000x reference)
.LBB0_691:
	s_add_i32 s6, s0, 2
	s_add_i32 s7, 0, 0x10000
	s_cmp_eq_u32 s44, s0
	v_lshl_add_u64 v[100:101], v[98:99], 0, s[84:85]
	s_cselect_b64 vcc, -1, 0
	v_add_u32_e32 v104, s7, v176
	v_cndmask_b32_e32 v175, v101, v165, vcc
	v_cndmask_b32_e32 v174, v100, v164, vcc
	ds_read_b128 v[100:103], v104
	ds_read_b128 v[138:141], v104 offset:1024
	ds_read_b128 v[142:145], v104 offset:2048
	ds_read_b128 v[166:169], v104 offset:3072
	s_cselect_b32 s0, s22, s4
	s_cselect_b32 s1, s23, s5
	v_lshl_add_u64 v[104:105], v[98:99], 0, v[156:157]
	s_add_i32 m0, s10, 0xc000
	ds_read_b128 v[170:173], v178
	ds_read_b128 v[180:183], v178 offset:1024
	ds_read_b128 v[184:187], v178 offset:2048
	ds_read_b128 v[188:191], v178 offset:3072
	ds_read_b128 v[192:195], v178 offset:4096
	ds_read_b128 v[196:199], v178 offset:5120
	ds_read_b128 v[200:203], v178 offset:6144
	ds_read_b128 v[204:207], v178 offset:7168
	global_load_lds_dwordx4 v[104:105], off
	v_lshl_add_u64 v[104:105], v[98:99], 0, v[160:161]
	s_add_i32 m0, s10, 0xe000
	s_nop 0
	global_load_lds_dwordx4 v[104:105], off
	s_waitcnt lgkmcnt(8)
	s_barrier
	s_waitcnt lgkmcnt(0)
	s_waitcnt lgkmcnt(0)
	v_mfma_f32_16x16x32_bf16 v[134:137], v[100:103], v[170:173], v[134:137]
	v_mfma_f32_16x16x32_bf16 v[130:133], v[142:145], v[170:173], v[130:133]
	v_mfma_f32_16x16x32_bf16 v[126:129], v[100:103], v[184:187], v[126:129]
	v_mfma_f32_16x16x32_bf16 v[122:125], v[142:145], v[184:187], v[122:125]
	v_mfma_f32_16x16x32_bf16 v[118:121], v[100:103], v[192:195], v[118:121]
	v_mfma_f32_16x16x32_bf16 v[114:117], v[142:145], v[192:195], v[114:117]
	v_mfma_f32_16x16x32_bf16 v[110:113], v[100:103], v[200:203], v[110:113]
	v_mfma_f32_16x16x32_bf16 v[104:107], v[142:145], v[200:203], v[106:109]
	v_mfma_f32_16x16x32_bf16 v[134:137], v[138:141], v[180:183], v[134:137]
	v_mfma_f32_16x16x32_bf16 v[130:133], v[166:169], v[180:183], v[130:133]
	v_mfma_f32_16x16x32_bf16 v[126:129], v[138:141], v[188:191], v[126:129]
	v_mfma_f32_16x16x32_bf16 v[122:125], v[166:169], v[188:191], v[122:125]
	v_mfma_f32_16x16x32_bf16 v[118:121], v[138:141], v[196:199], v[118:121]
	v_mfma_f32_16x16x32_bf16 v[114:117], v[166:169], v[196:199], v[114:117]
	v_mfma_f32_16x16x32_bf16 v[110:113], v[138:141], v[204:207], v[110:113]
	v_mfma_f32_16x16x32_bf16 v[104:107], v[166:169], v[204:207], v[104:107]
	s_barrier
	s_add_i32 s36, 0, 0x14000
	s_add_i32 s7, s7, s9
	v_add_u32_e32 v108, s36, v176
	v_lshl_add_u64 v[242:243], s[0:1], 0, v[148:149]
	s_mov_b32 m0, s7
	ds_read_b128 v[208:211], v108
	ds_read_b128 v[212:215], v108 offset:1024
	ds_read_b128 v[216:219], v108 offset:2048
	ds_read_b128 v[238:241], v108 offset:3072
	global_load_lds_dwordx4 v[242:243], off
	v_lshl_add_u64 v[244:245], s[0:1], 0, v[152:153]
	s_add_i32 m0, s7, 0x2000
	s_nop 0
	global_load_lds_dwordx4 v[244:245], off
	s_barrier
	s_waitcnt lgkmcnt(0)
	s_waitcnt lgkmcnt(0)
	v_mfma_f32_16x16x32_bf16 v[62:65], v[208:211], v[170:173], v[62:65]
	v_mfma_f32_16x16x32_bf16 v[58:61], v[216:219], v[170:173], v[58:61]
	v_mfma_f32_16x16x32_bf16 v[54:57], v[208:211], v[184:187], v[54:57]
	v_mfma_f32_16x16x32_bf16 v[50:53], v[216:219], v[184:187], v[50:53]
	v_mfma_f32_16x16x32_bf16 v[46:49], v[208:211], v[192:195], v[46:49]
	v_mfma_f32_16x16x32_bf16 v[42:45], v[216:219], v[192:195], v[42:45]
	v_mfma_f32_16x16x32_bf16 v[38:41], v[208:211], v[200:203], v[38:41]
	v_mfma_f32_16x16x32_bf16 v[34:37], v[216:219], v[200:203], v[34:37]
	v_mfma_f32_16x16x32_bf16 v[62:65], v[212:215], v[180:183], v[62:65]
	v_mfma_f32_16x16x32_bf16 v[58:61], v[238:241], v[180:183], v[58:61]
	v_mfma_f32_16x16x32_bf16 v[54:57], v[212:215], v[188:191], v[54:57]
	v_mfma_f32_16x16x32_bf16 v[50:53], v[238:241], v[188:191], v[50:53]
	v_mfma_f32_16x16x32_bf16 v[46:49], v[212:215], v[196:199], v[46:49]
	v_mfma_f32_16x16x32_bf16 v[42:45], v[238:241], v[196:199], v[42:45]
	v_mfma_f32_16x16x32_bf16 v[38:41], v[212:215], v[204:207], v[38:41]
	v_mfma_f32_16x16x32_bf16 v[34:37], v[238:241], v[204:207], v[34:37]
	s_mov_b32 m0, s10
	v_lshl_add_u64 v[246:247], v[174:175], 0, v[146:147]
	s_barrier
	ds_read_b128 v[170:173], v178 offset:16384
	ds_read_b128 v[180:183], v178 offset:17408
	ds_read_b128 v[184:187], v178 offset:18432
	ds_read_b128 v[188:191], v178 offset:19456
	ds_read_b128 v[192:195], v178 offset:20480
	ds_read_b128 v[196:199], v178 offset:21504
	ds_read_b128 v[200:203], v178 offset:22528
	ds_read_b128 v[204:207], v178 offset:23552
	global_load_lds_dwordx4 v[246:247], off
	v_lshl_add_u64 v[248:249], v[174:175], 0, v[150:151]
	s_mov_b32 m0, s11
	s_nop 0
	global_load_lds_dwordx4 v[248:249], off
	s_barrier
	s_waitcnt lgkmcnt(0)
	s_waitcnt lgkmcnt(0)
	v_mfma_f32_16x16x32_bf16 v[94:97], v[100:103], v[170:173], v[94:97]
	v_mfma_f32_16x16x32_bf16 v[90:93], v[142:145], v[170:173], v[90:93]
	v_mfma_f32_16x16x32_bf16 v[86:89], v[100:103], v[184:187], v[86:89]
	v_mfma_f32_16x16x32_bf16 v[82:85], v[142:145], v[184:187], v[82:85]
	v_mfma_f32_16x16x32_bf16 v[78:81], v[100:103], v[192:195], v[78:81]
	v_mfma_f32_16x16x32_bf16 v[74:77], v[142:145], v[192:195], v[74:77]
	v_mfma_f32_16x16x32_bf16 v[70:73], v[100:103], v[200:203], v[70:73]
	v_mfma_f32_16x16x32_bf16 v[66:69], v[142:145], v[200:203], v[66:69]
	v_mfma_f32_16x16x32_bf16 v[94:97], v[138:141], v[180:183], v[94:97]
	v_mfma_f32_16x16x32_bf16 v[90:93], v[166:169], v[180:183], v[90:93]
	v_mfma_f32_16x16x32_bf16 v[86:89], v[138:141], v[188:191], v[86:89]
	v_mfma_f32_16x16x32_bf16 v[82:85], v[166:169], v[188:191], v[82:85]
	v_mfma_f32_16x16x32_bf16 v[78:81], v[138:141], v[196:199], v[78:81]
	v_mfma_f32_16x16x32_bf16 v[74:77], v[166:169], v[196:199], v[74:77]
	v_mfma_f32_16x16x32_bf16 v[70:73], v[138:141], v[204:207], v[70:73]
	v_mfma_f32_16x16x32_bf16 v[66:69], v[166:169], v[204:207], v[66:69]
	s_barrier
	s_add_u32 s0, s0, s94
	s_addc_u32 s1, s1, 0
	s_add_i32 s7, s36, s9
	v_lshl_add_u64 v[230:231], s[0:1], 0, v[148:149]
	s_mov_b32 m0, s7
	v_lshl_add_u64 v[224:225], s[0:1], 0, v[152:153]
	global_load_lds_dwordx4 v[230:231], off
	s_add_i32 m0, s7, 0x2000
	s_nop 0
	global_load_lds_dwordx4 v[224:225], off
	s_waitcnt vmcnt(6)
	s_barrier
	v_mfma_f32_16x16x32_bf16 v[30:33], v[208:211], v[170:173], v[30:33]
	v_mfma_f32_16x16x32_bf16 v[26:29], v[216:219], v[170:173], v[26:29]
	v_mfma_f32_16x16x32_bf16 v[22:25], v[208:211], v[184:187], v[22:25]
	v_mfma_f32_16x16x32_bf16 v[18:21], v[216:219], v[184:187], v[18:21]
	v_mfma_f32_16x16x32_bf16 v[14:17], v[208:211], v[192:195], v[14:17]
	v_mfma_f32_16x16x32_bf16 v[10:13], v[216:219], v[192:195], v[10:13]
	v_mfma_f32_16x16x32_bf16 v[6:9], v[208:211], v[200:203], v[6:9]
	v_mfma_f32_16x16x32_bf16 v[2:5], v[216:219], v[200:203], v[2:5]
	v_mfma_f32_16x16x32_bf16 v[30:33], v[212:215], v[180:183], v[30:33]
	v_mfma_f32_16x16x32_bf16 v[26:29], v[238:241], v[180:183], v[26:29]
	v_mfma_f32_16x16x32_bf16 v[22:25], v[212:215], v[188:191], v[22:25]
	v_mfma_f32_16x16x32_bf16 v[18:21], v[238:241], v[188:191], v[18:21]
	v_mfma_f32_16x16x32_bf16 v[14:17], v[212:215], v[196:199], v[14:17]
	v_mfma_f32_16x16x32_bf16 v[10:13], v[238:241], v[196:199], v[10:13]
	v_mfma_f32_16x16x32_bf16 v[6:9], v[212:215], v[204:207], v[6:9]
	v_mfma_f32_16x16x32_bf16 v[2:5], v[238:241], v[204:207], v[2:5]
	s_add_i32 s0, 0, 0x18000
	v_add_u32_e32 v108, s0, v176
	s_barrier
	ds_read_b128 v[100:103], v108
	ds_read_b128 v[138:141], v108 offset:1024
	ds_read_b128 v[142:145], v108 offset:2048
	ds_read_b128 v[166:169], v108 offset:3072
	v_lshl_add_u64 v[108:109], v[174:175], 0, s[94:95]
	s_mov_b32 m0, s8
	v_lshl_add_u64 v[174:175], v[108:109], 0, v[146:147]
	ds_read_b128 v[170:173], v178 offset:32768
	ds_read_b128 v[180:183], v178 offset:33792
	ds_read_b128 v[184:187], v178 offset:34816
	ds_read_b128 v[188:191], v178 offset:35840
	ds_read_b128 v[192:195], v178 offset:36864
	ds_read_b128 v[196:199], v178 offset:37888
	ds_read_b128 v[200:203], v178 offset:38912
	ds_read_b128 v[204:207], v178 offset:39936
	global_load_lds_dwordx4 v[174:175], off
	v_lshl_add_u64 v[108:109], v[108:109], 0, v[150:151]
	s_mov_b32 m0, s2
	s_nop 0
	global_load_lds_dwordx4 v[108:109], off
	s_waitcnt lgkmcnt(8)
	s_barrier
	s_waitcnt lgkmcnt(0)
	s_waitcnt lgkmcnt(0)
	v_mfma_f32_16x16x32_bf16 v[134:137], v[100:103], v[170:173], v[134:137]
	v_mfma_f32_16x16x32_bf16 v[130:133], v[142:145], v[170:173], v[130:133]
	v_mfma_f32_16x16x32_bf16 v[126:129], v[100:103], v[184:187], v[126:129]
	v_mfma_f32_16x16x32_bf16 v[122:125], v[142:145], v[184:187], v[122:125]
	v_mfma_f32_16x16x32_bf16 v[118:121], v[100:103], v[192:195], v[118:121]
	v_mfma_f32_16x16x32_bf16 v[114:117], v[142:145], v[192:195], v[114:117]
	v_mfma_f32_16x16x32_bf16 v[108:111], v[100:103], v[200:203], v[110:113]
	v_mfma_f32_16x16x32_bf16 v[104:107], v[142:145], v[200:203], v[104:107]
	v_mfma_f32_16x16x32_bf16 v[134:137], v[138:141], v[180:183], v[134:137]
	v_mfma_f32_16x16x32_bf16 v[130:133], v[166:169], v[180:183], v[130:133]
	v_mfma_f32_16x16x32_bf16 v[126:129], v[138:141], v[188:191], v[126:129]
	v_mfma_f32_16x16x32_bf16 v[122:125], v[166:169], v[188:191], v[122:125]
	v_mfma_f32_16x16x32_bf16 v[118:121], v[138:141], v[196:199], v[118:121]
	v_mfma_f32_16x16x32_bf16 v[114:117], v[166:169], v[196:199], v[114:117]
	v_mfma_f32_16x16x32_bf16 v[110:113], v[138:141], v[204:207], v[108:111]
	v_mfma_f32_16x16x32_bf16 v[106:109], v[166:169], v[204:207], v[104:107]
	s_barrier
	s_add_i32 s1, 0, 0x1c000
	v_add_u32_e32 v104, s1, v176
	s_add_i32 s0, s0, s9
	ds_read_b128 v[208:211], v104
	ds_read_b128 v[212:215], v104 offset:1024
	ds_read_b128 v[216:219], v104 offset:2048
	ds_read_b128 v[238:241], v104 offset:3072
	s_add_i32 m0, s0, 0xffffff80
	s_nop 0
	global_load_lds_dwordx4 v[242:243], off offset:128
	s_add_i32 m0, s0, 0x1f80
	s_nop 0
	global_load_lds_dwordx4 v[244:245], off offset:128
	s_barrier
	s_waitcnt lgkmcnt(0)
	s_waitcnt lgkmcnt(0)
	v_mfma_f32_16x16x32_bf16 v[62:65], v[208:211], v[170:173], v[62:65]
	v_mfma_f32_16x16x32_bf16 v[58:61], v[216:219], v[170:173], v[58:61]
	v_mfma_f32_16x16x32_bf16 v[54:57], v[208:211], v[184:187], v[54:57]
	v_mfma_f32_16x16x32_bf16 v[50:53], v[216:219], v[184:187], v[50:53]
	v_mfma_f32_16x16x32_bf16 v[46:49], v[208:211], v[192:195], v[46:49]
	v_mfma_f32_16x16x32_bf16 v[42:45], v[216:219], v[192:195], v[42:45]
	v_mfma_f32_16x16x32_bf16 v[38:41], v[208:211], v[200:203], v[38:41]
	v_mfma_f32_16x16x32_bf16 v[34:37], v[216:219], v[200:203], v[34:37]
	v_mfma_f32_16x16x32_bf16 v[62:65], v[212:215], v[180:183], v[62:65]
	v_mfma_f32_16x16x32_bf16 v[58:61], v[238:241], v[180:183], v[58:61]
	v_mfma_f32_16x16x32_bf16 v[54:57], v[212:215], v[188:191], v[54:57]
	v_mfma_f32_16x16x32_bf16 v[50:53], v[238:241], v[188:191], v[50:53]
	v_mfma_f32_16x16x32_bf16 v[46:49], v[212:215], v[196:199], v[46:49]
	v_mfma_f32_16x16x32_bf16 v[42:45], v[238:241], v[196:199], v[42:45]
	v_mfma_f32_16x16x32_bf16 v[38:41], v[212:215], v[204:207], v[38:41]
	v_mfma_f32_16x16x32_bf16 v[34:37], v[238:241], v[204:207], v[34:37]
	s_add_i32 m0, s54, 0xffffff80
	s_barrier
	ds_read_b128 v[170:173], v178 offset:49152
	ds_read_b128 v[180:183], v178 offset:50176
	ds_read_b128 v[184:187], v178 offset:51200
	ds_read_b128 v[188:191], v178 offset:52224
	ds_read_b128 v[192:195], v178 offset:53248
	ds_read_b128 v[196:199], v178 offset:54272
	ds_read_b128 v[200:203], v178 offset:55296
	ds_read_b128 v[204:207], v178 offset:56320
	global_load_lds_dwordx4 v[246:247], off offset:128
	s_add_i32 m0, s3, 0xffffff80
	s_nop 0
	global_load_lds_dwordx4 v[248:249], off offset:128
	s_barrier
	s_waitcnt lgkmcnt(0)
	s_waitcnt lgkmcnt(0)
	v_mfma_f32_16x16x32_bf16 v[94:97], v[100:103], v[170:173], v[94:97]
	v_mfma_f32_16x16x32_bf16 v[90:93], v[142:145], v[170:173], v[90:93]
	v_mfma_f32_16x16x32_bf16 v[86:89], v[100:103], v[184:187], v[86:89]
	v_mfma_f32_16x16x32_bf16 v[82:85], v[142:145], v[184:187], v[82:85]
	v_mfma_f32_16x16x32_bf16 v[78:81], v[100:103], v[192:195], v[78:81]
	v_mfma_f32_16x16x32_bf16 v[74:77], v[142:145], v[192:195], v[74:77]
	v_mfma_f32_16x16x32_bf16 v[70:73], v[100:103], v[200:203], v[70:73]
	v_mfma_f32_16x16x32_bf16 v[66:69], v[142:145], v[200:203], v[66:69]
	v_mfma_f32_16x16x32_bf16 v[94:97], v[138:141], v[180:183], v[94:97]
	v_mfma_f32_16x16x32_bf16 v[90:93], v[166:169], v[180:183], v[90:93]
	v_mfma_f32_16x16x32_bf16 v[86:89], v[138:141], v[188:191], v[86:89]
	v_mfma_f32_16x16x32_bf16 v[82:85], v[166:169], v[188:191], v[82:85]
	v_mfma_f32_16x16x32_bf16 v[78:81], v[138:141], v[196:199], v[78:81]
	v_mfma_f32_16x16x32_bf16 v[74:77], v[166:169], v[196:199], v[74:77]
	v_mfma_f32_16x16x32_bf16 v[70:73], v[138:141], v[204:207], v[70:73]
	v_mfma_f32_16x16x32_bf16 v[66:69], v[166:169], v[204:207], v[66:69]
	s_barrier
	s_add_i32 s0, s1, s9
	s_add_i32 m0, s0, 0xffffff80
	s_nop 0
	global_load_lds_dwordx4 v[230:231], off offset:128
	s_add_i32 m0, s0, 0x1f80
	s_nop 0
	global_load_lds_dwordx4 v[224:225], off offset:128
	s_waitcnt vmcnt(6)
	s_barrier
	v_mfma_f32_16x16x32_bf16 v[30:33], v[208:211], v[170:173], v[30:33]
	v_mfma_f32_16x16x32_bf16 v[26:29], v[216:219], v[170:173], v[26:29]
	v_mfma_f32_16x16x32_bf16 v[22:25], v[208:211], v[184:187], v[22:25]
	v_mfma_f32_16x16x32_bf16 v[18:21], v[216:219], v[184:187], v[18:21]
	v_mfma_f32_16x16x32_bf16 v[14:17], v[208:211], v[192:195], v[14:17]
	v_mfma_f32_16x16x32_bf16 v[10:13], v[216:219], v[192:195], v[10:13]
	v_mfma_f32_16x16x32_bf16 v[6:9], v[208:211], v[200:203], v[6:9]
	v_mfma_f32_16x16x32_bf16 v[2:5], v[216:219], v[200:203], v[2:5]
	v_mfma_f32_16x16x32_bf16 v[30:33], v[212:215], v[180:183], v[30:33]
	v_mfma_f32_16x16x32_bf16 v[26:29], v[238:241], v[180:183], v[26:29]
	v_mfma_f32_16x16x32_bf16 v[22:25], v[212:215], v[188:191], v[22:25]
	v_mfma_f32_16x16x32_bf16 v[18:21], v[238:241], v[188:191], v[18:21]
	v_mfma_f32_16x16x32_bf16 v[14:17], v[212:215], v[196:199], v[14:17]
	v_mfma_f32_16x16x32_bf16 v[10:13], v[238:241], v[196:199], v[10:13]
	v_mfma_f32_16x16x32_bf16 v[6:9], v[212:215], v[204:207], v[6:9]
	v_mfma_f32_16x16x32_bf16 v[2:5], v[238:241], v[204:207], v[2:5]
	s_add_u32 s4, s4, 0x100
	s_addc_u32 s5, s5, 0
	v_lshl_add_u64 v[98:99], v[98:99], 0, s[86:87]
	s_cmp_ge_u32 s6, s13
	s_mov_b32 s0, s6
	s_barrier
	s_cbranch_scc0 .LBB0_691
	s_and_b64 vcc, exec, s[42:43]
	s_cbranch_vccz .LBB0_694
	ds_read2st64_b32 v[98:99], v179 offset0:6 offset1:7
	ds_read2st64_b32 v[102:103], v179 offset0:4 offset1:5
	ds_read2st64_b32 v[104:105], v179 offset0:2 offset1:3
	ds_read2st64_b32 v[100:101], v179 offset1:1
	v_cmp_lt_i32_e32 vcc, v227, v222
	s_mov_b32 s0, 0x358637bd
	s_mov_b32 s4, 0x3a800000
	v_cndmask_b32_e32 v138, v221, v227, vcc
	v_cmp_lt_i32_e32 vcc, v228, v222
	v_lshlrev_b32_e32 v142, 2, v138
	s_waitcnt lgkmcnt(0)
	v_mov_b32_e32 v139, v101
	s_nop 1
	v_permlane16_swap_b32_e32 v139, v101
	v_cndmask_b32_e32 v138, v221, v228, vcc
	v_lshlrev_b32_e32 v143, 2, v138
	v_mov_b32_e32 v138, v100
	s_nop 1
	v_permlane16_swap_b32_e32 v138, v100
	s_mov_b32 s6, 0x45800000
	s_waitcnt lgkmcnt(0)
	v_pk_add_f32 v[100:101], v[100:101], v[138:139]
	v_mov_b32_e32 v138, v100
	s_nop 1
	v_permlane32_swap_b32_e32 v138, v100
	v_mov_b32_e32 v139, v101
	s_nop 1
	v_permlane32_swap_b32_e32 v139, v101
	s_waitcnt lgkmcnt(0)
	v_pk_add_f32 v[138:139], v[100:101], v[138:139]
	v_mov_b64_e32 v[100:101], s[0:1]
	v_pk_fma_f32 v[138:139], v[138:139], s[4:5], v[100:101] op_sel_hi:[1,0,0]
	s_nop 0
	v_mul_f32_e32 v140, 0x4b800000, v138
	v_cmp_gt_f32_e64 s[0:1], s88, v138
	v_cmp_gt_f32_e32 vcc, s88, v139
	s_nop 0
	v_cndmask_b32_e64 v138, v138, v140, s[0:1]
	v_mul_f32_e32 v140, 0x4b800000, v139
	v_cndmask_b32_e32 v139, v139, v140, vcc
	v_rsq_f32_e32 v138, v138
	v_rsq_f32_e32 v139, v139
	s_nop 0
	v_pk_mul_f32 v[140:141], v[138:139], s[6:7] op_sel_hi:[1,0]
	s_nop 0
	v_cndmask_b32_e64 v174, v138, v140, s[0:1]
	v_cndmask_b32_e32 v175, v139, v141, vcc
	v_mov_b32_e32 v138, v104
	s_nop 1
	v_permlane16_swap_b32_e32 v138, v104
	v_mov_b32_e32 v139, v105
	s_nop 1
	v_permlane16_swap_b32_e32 v139, v105
	s_waitcnt lgkmcnt(0)
	v_pk_add_f32 v[104:105], v[104:105], v[138:139]
	v_mov_b32_e32 v138, v104
	s_nop 1
	v_permlane32_swap_b32_e32 v138, v104
	v_mov_b32_e32 v139, v105
	s_nop 1
	v_permlane32_swap_b32_e32 v139, v105
	s_waitcnt lgkmcnt(0)
	v_pk_add_f32 v[104:105], v[104:105], v[138:139]
	s_nop 0
	v_pk_fma_f32 v[104:105], v[104:105], s[4:5], v[100:101] op_sel_hi:[1,0,0]
	s_nop 0
	v_mul_f32_e32 v138, 0x4b800000, v104
	v_cmp_gt_f32_e64 s[0:1], s88, v104
	v_cmp_gt_f32_e32 vcc, s88, v105
	s_nop 0
	v_cndmask_b32_e64 v104, v104, v138, s[0:1]
	v_mul_f32_e32 v138, 0x4b800000, v105
	v_cndmask_b32_e32 v105, v105, v138, vcc
	v_rsq_f32_e32 v104, v104
	v_rsq_f32_e32 v105, v105
	s_nop 0
	v_pk_mul_f32 v[138:139], v[104:105], s[6:7] op_sel_hi:[1,0]
	s_nop 0
	v_cndmask_b32_e64 v172, v104, v138, s[0:1]
	v_cndmask_b32_e32 v173, v105, v139, vcc
	v_mov_b32_e32 v104, v102
	s_nop 1
	v_permlane16_swap_b32_e32 v104, v102
	v_mov_b32_e32 v105, v103
	s_nop 1
	v_permlane16_swap_b32_e32 v105, v103
	s_waitcnt lgkmcnt(0)
	v_pk_add_f32 v[102:103], v[102:103], v[104:105]
	v_mov_b32_e32 v104, v102
	s_nop 1
	v_permlane32_swap_b32_e32 v104, v102
	v_mov_b32_e32 v105, v103
	s_nop 1
	v_permlane32_swap_b32_e32 v105, v103
	s_waitcnt lgkmcnt(0)
	v_pk_add_f32 v[102:103], v[102:103], v[104:105]
	s_nop 0
	v_pk_fma_f32 v[102:103], v[102:103], s[4:5], v[100:101] op_sel_hi:[1,0,0]
	s_nop 0
	v_mul_f32_e32 v104, 0x4b800000, v102
	v_cmp_gt_f32_e64 s[0:1], s88, v102
	v_cmp_gt_f32_e32 vcc, s88, v103
	s_nop 0
	v_cndmask_b32_e64 v102, v102, v104, s[0:1]
	v_mul_f32_e32 v104, 0x4b800000, v103
	v_cndmask_b32_e32 v103, v103, v104, vcc
	v_rsq_f32_e32 v102, v102
	v_rsq_f32_e32 v103, v103
	s_nop 0
	v_pk_mul_f32 v[104:105], v[102:103], s[6:7] op_sel_hi:[1,0]
	s_nop 0
	v_cndmask_b32_e64 v170, v102, v104, s[0:1]
	v_cndmask_b32_e32 v171, v103, v105, vcc
	v_mov_b32_e32 v102, v98
	s_nop 1
	v_permlane16_swap_b32_e32 v102, v98
	v_mov_b32_e32 v103, v99
	s_nop 1
	v_permlane16_swap_b32_e32 v103, v99
	s_waitcnt lgkmcnt(0)
	v_pk_add_f32 v[98:99], v[98:99], v[102:103]
	v_mov_b32_e32 v102, v98
	s_nop 1
	v_permlane32_swap_b32_e32 v102, v98
	v_mov_b32_e32 v103, v99
	s_nop 1
	v_permlane32_swap_b32_e32 v103, v99
	s_waitcnt lgkmcnt(0)
	v_pk_add_f32 v[98:99], v[98:99], v[102:103]
	s_nop 0
	v_pk_fma_f32 v[98:99], v[98:99], s[4:5], v[100:101] op_sel_hi:[1,0,0]
	s_nop 0
	v_mul_f32_e32 v100, 0x4b800000, v98
	v_cmp_gt_f32_e64 s[0:1], s88, v98
	v_cmp_gt_f32_e32 vcc, s88, v99
	s_nop 0
	v_cndmask_b32_e64 v98, v98, v100, s[0:1]
	v_mul_f32_e32 v100, 0x4b800000, v99
	v_cndmask_b32_e32 v99, v99, v100, vcc
	v_rsq_f32_e32 v98, v98
	v_rsq_f32_e32 v99, v99
	s_nop 0
	v_pk_mul_f32 v[100:101], v[98:99], s[6:7] op_sel_hi:[1,0]
	s_nop 0
	v_cndmask_b32_e64 v168, v98, v100, s[0:1]
	v_cndmask_b32_e32 v169, v99, v101, vcc
	s_branch .LBB0_695
